# v29: P2 stream loop - first half-iteration waits after a tile epilogue relaxed to vmcnt(8+stores) so store acks are not waited there
# baseline (speedup 1.0000x reference)
.LBB0_367:
	s_lshl_b32 s0, s0, 12
	v_mov_b32_e32 v131, v196
	s_lshl_b32 s36, s1, 13
	s_and_b32 s37, s0, 0x3000
	v_lshl_add_u64 v[10:11], s[42:43], 0, v[130:131]
	v_mov_b32_e32 v133, v196
	s_add_u32 s0, s42, 0x40080
	v_lshl_add_u64 v[12:13], s[42:43], 0, v[132:133]
	s_addc_u32 s1, s43, 0
	s_add_i32 m0, s33, 0x18000
	v_lshl_add_u64 v[10:11], v[10:11], 0, s[48:49]
	v_lshl_add_u64 v[14:15], s[16:17], 0, v[130:131]
	s_waitcnt vmcnt(2)
	s_barrier
	global_load_lds_dwordx4 v[10:11], off
	v_lshl_add_u64 v[10:11], v[12:13], 0, s[48:49]
	s_add_i32 m0, s33, 0x1a000
	s_add_i32 s71, s33, 0x8000
	v_lshl_add_u64 v[16:17], s[16:17], 0, v[132:133]
	global_load_lds_dwordx4 v[10:11], off
	v_lshl_add_u64 v[10:11], v[14:15], 0, s[48:49]
	s_mov_b32 m0, s71
	s_add_i32 s79, s33, 0xa000
	global_load_lds_dwordx4 v[10:11], off
	v_lshl_add_u64 v[10:11], v[16:17], 0, s[48:49]
	s_mov_b32 m0, s79
	v_and_b32_e32 v9, 15, v3
	global_load_lds_dwordx4 v[10:11], off
	s_add_i32 m0, s33, 0x1c000
	v_lshl_add_u64 v[10:11], s[0:1], 0, v[130:131]
	global_load_lds_dwordx4 v[10:11], off
	v_lshl_add_u64 v[10:11], s[0:1], 0, v[132:133]
	s_add_i32 m0, s33, 0x1e000
	v_lshlrev_b32_e32 v9, 6, v9
	global_load_lds_dwordx4 v[10:11], off
	v_and_b32_e32 v10, 48, v3
	v_lshlrev_b32_e32 v3, 2, v3
	v_and_b32_e32 v3, 32, v3
	v_or_b32_e32 v11, v9, v10
	v_bitop3_b32 v9, v9, v3, v10 bitop3:0x36
	v_or_b32_e32 v156, s37, v9
	v_lshlrev_b32_e32 v9, 14, v2
	v_and_b32_e32 v9, 0xffff8000, v9
	v_lshl_add_u32 v4, v4, 11, v9
	v_and_b32_e32 v2, 1, v2
	v_lshl_or_b32 v2, v2, 6, v4
	v_lshl_add_u32 v134, v5, 1, v2
	v_lshlrev_b32_e32 v2, 14, v6
	v_and_b32_e32 v2, 0xffff8000, v2
	s_waitcnt vmcnt(6)
	v_lshl_add_u32 v2, v7, 11, v2
	v_and_b32_e32 v4, 1, v6
	v_bitop3_b32 v3, v11, s36, v3 bitop3:0xde
	v_lshl_or_b32 v2, v4, 6, v2
	v_mov_b32_e32 v135, v196
	v_lshl_add_u32 v136, v8, 1, v2
	v_mov_b32_e32 v137, v196
	v_add_u32_e32 v157, 0, v3
	v_readlane_b32 s78, v253, 0
	s_mov_b64 s[0:1], s[16:17]
	s_barrier
	s_mov_b32 s67, 0
	s_branch .LBB0_369

.LBB0_374:
	s_add_u32 s42, s16, 0xfffc0080
	s_addc_u32 s43, s17, -1
	s_add_i32 s75, 0, 0x10000
	s_cmp_eq_u32 vcc_hi, 12
	s_cselect_b32 s45, s1, s43
	s_cselect_b32 s44, s0, s42
	s_cselect_b32 s43, s41, vcc_lo
	s_cselect_b32 s42, s40, s74
	s_add_i32 s81, 0, 0x14000
	v_add_u32_e32 v150, s75, v156
	v_add_u32_e32 v154, s81, v156
	ds_read_b128 v[138:141], v150
	ds_read_b128 v[142:145], v150 offset:1024
	ds_read_b128 v[146:149], v150 offset:2048
	ds_read_b128 v[150:153], v150 offset:3072
	ds_read_b128 v[158:161], v154
	ds_read_b128 v[162:165], v154 offset:1024
	ds_read_b128 v[166:169], v154 offset:2048
	ds_read_b128 v[170:173], v154 offset:3072
	v_lshl_add_u64 v[154:155], s[16:17], 0, v[134:135]
	s_add_i32 m0, s33, 0xc000
	ds_read_b128 v[174:177], v157
	ds_read_b128 v[178:181], v157 offset:1024
	ds_read_b128 v[182:185], v157 offset:2048
	ds_read_b128 v[186:189], v157 offset:3072
	ds_read_b128 v[190:193], v157 offset:4096
	ds_read_b128 v[202:205], v157 offset:5120
	ds_read_b128 v[206:209], v157 offset:6144
	ds_read_b128 v[210:213], v157 offset:7168
	global_load_lds_dwordx4 v[154:155], off
	v_lshl_add_u64 v[154:155], s[16:17], 0, v[136:137]
	s_add_i32 m0, s33, 0xe000
	s_nop 0
	global_load_lds_dwordx4 v[154:155], off
	s_cmp_lg_u32 s67, 0
	s_cbranch_scc1 .Lp2_wa_rel
	s_waitcnt vmcnt(8)
.Lp2_wa_done:
	s_waitcnt lgkmcnt(0)
	s_barrier
	s_setprio 1
	s_waitcnt lgkmcnt(0)
	v_mfma_f32_16x16x32_bf16 v[126:129], v[138:141], v[174:177], v[126:129]
	v_mfma_f32_16x16x32_bf16 v[122:125], v[146:149], v[174:177], v[122:125]
	v_mfma_f32_16x16x32_bf16 v[114:117], v[138:141], v[182:185], v[114:117]
	v_mfma_f32_16x16x32_bf16 v[106:109], v[146:149], v[182:185], v[106:109]
	v_mfma_f32_16x16x32_bf16 v[98:101], v[138:141], v[190:193], v[98:101]
	v_mfma_f32_16x16x32_bf16 v[90:93], v[146:149], v[190:193], v[90:93]
	v_mfma_f32_16x16x32_bf16 v[82:85], v[138:141], v[206:209], v[82:85]
	v_mfma_f32_16x16x32_bf16 v[74:77], v[146:149], v[206:209], v[74:77]
	v_mfma_f32_16x16x32_bf16 v[126:129], v[142:145], v[178:181], v[126:129]
	v_mfma_f32_16x16x32_bf16 v[122:125], v[150:153], v[178:181], v[122:125]
	v_mfma_f32_16x16x32_bf16 v[114:117], v[142:145], v[186:189], v[114:117]
	v_mfma_f32_16x16x32_bf16 v[106:109], v[150:153], v[186:189], v[106:109]
	v_mfma_f32_16x16x32_bf16 v[98:101], v[142:145], v[202:205], v[98:101]
	v_mfma_f32_16x16x32_bf16 v[90:93], v[150:153], v[202:205], v[90:93]
	v_mfma_f32_16x16x32_bf16 v[82:85], v[142:145], v[210:213], v[82:85]
	v_mfma_f32_16x16x32_bf16 v[74:77], v[150:153], v[210:213], v[74:77]
	s_setprio 0
	s_setprio 1
	v_mfma_f32_16x16x32_bf16 v[118:121], v[158:161], v[174:177], v[118:121]
	v_mfma_f32_16x16x32_bf16 v[110:113], v[166:169], v[174:177], v[110:113]
	v_mfma_f32_16x16x32_bf16 v[102:105], v[158:161], v[182:185], v[102:105]
	v_mfma_f32_16x16x32_bf16 v[94:97], v[166:169], v[182:185], v[94:97]
	v_mfma_f32_16x16x32_bf16 v[86:89], v[158:161], v[190:193], v[86:89]
	v_mfma_f32_16x16x32_bf16 v[78:81], v[166:169], v[190:193], v[78:81]
	v_mfma_f32_16x16x32_bf16 v[70:73], v[158:161], v[206:209], v[70:73]
	v_mfma_f32_16x16x32_bf16 v[66:69], v[166:169], v[206:209], v[66:69]
	v_mfma_f32_16x16x32_bf16 v[118:121], v[162:165], v[178:181], v[118:121]
	v_mfma_f32_16x16x32_bf16 v[110:113], v[170:173], v[178:181], v[110:113]
	v_mfma_f32_16x16x32_bf16 v[102:105], v[162:165], v[186:189], v[102:105]
	v_mfma_f32_16x16x32_bf16 v[94:97], v[170:173], v[186:189], v[94:97]
	v_mfma_f32_16x16x32_bf16 v[86:89], v[162:165], v[202:205], v[86:89]
	v_mfma_f32_16x16x32_bf16 v[78:81], v[170:173], v[202:205], v[78:81]
	v_mfma_f32_16x16x32_bf16 v[70:73], v[162:165], v[210:213], v[70:73]
	v_mfma_f32_16x16x32_bf16 v[66:69], v[170:173], v[210:213], v[66:69]
	s_setprio 0
	s_barrier
	s_add_i32 s75, s75, s15
	v_lshl_add_u64 v[154:155], s[42:43], 0, v[130:131]
	s_mov_b32 m0, s75
	ds_read_b128 v[174:177], v157 offset:16384
	ds_read_b128 v[178:181], v157 offset:17408
	ds_read_b128 v[182:185], v157 offset:18432
	ds_read_b128 v[186:189], v157 offset:19456
	ds_read_b128 v[190:193], v157 offset:20480
	ds_read_b128 v[202:205], v157 offset:21504
	ds_read_b128 v[206:209], v157 offset:22528
	ds_read_b128 v[210:213], v157 offset:23552
	global_load_lds_dwordx4 v[154:155], off
	s_add_i32 m0, s75, 0x2000
	s_add_u32 s76, s42, 0x40000
	v_lshl_add_u64 v[194:195], s[42:43], 0, v[132:133]
	s_addc_u32 s77, s43, 0
	s_add_i32 s75, s81, s15
	global_load_lds_dwordx4 v[194:195], off
	v_lshl_add_u64 v[198:199], s[76:77], 0, v[130:131]
	s_mov_b32 m0, s75
	v_lshl_add_u64 v[200:201], s[44:45], 0, v[132:133]
	global_load_lds_dwordx4 v[198:199], off
	v_lshl_add_u64 v[198:199], s[76:77], 0, v[132:133]
	s_add_i32 m0, s75, 0x2000
	s_nop 0
	global_load_lds_dwordx4 v[198:199], off
	v_lshl_add_u64 v[198:199], s[44:45], 0, v[130:131]
	s_mov_b32 m0, s33
	s_nop 0
	global_load_lds_dwordx4 v[198:199], off
	s_mov_b32 m0, s68
	s_nop 0
	global_load_lds_dwordx4 v[200:201], off
	s_cmp_lg_u32 s67, 0
	s_cbranch_scc1 .Lp2_wb_rel
	s_waitcnt vmcnt(8)
.Lp2_wb_done:
	s_mov_b32 s67, 0
	s_waitcnt lgkmcnt(0)
	s_barrier
	s_setprio 1
	s_waitcnt lgkmcnt(0)
	v_mfma_f32_16x16x32_bf16 v[62:65], v[138:141], v[174:177], v[62:65]
	v_mfma_f32_16x16x32_bf16 v[58:61], v[146:149], v[174:177], v[58:61]
	v_mfma_f32_16x16x32_bf16 v[50:53], v[138:141], v[182:185], v[50:53]
	v_mfma_f32_16x16x32_bf16 v[42:45], v[146:149], v[182:185], v[42:45]
	v_mfma_f32_16x16x32_bf16 v[34:37], v[138:141], v[190:193], v[34:37]
	v_mfma_f32_16x16x32_bf16 v[26:29], v[146:149], v[190:193], v[26:29]
	v_mfma_f32_16x16x32_bf16 v[18:21], v[138:141], v[206:209], v[18:21]
	v_mfma_f32_16x16x32_bf16 v[10:13], v[146:149], v[206:209], v[10:13]
	v_mfma_f32_16x16x32_bf16 v[62:65], v[142:145], v[178:181], v[62:65]
	v_mfma_f32_16x16x32_bf16 v[58:61], v[150:153], v[178:181], v[58:61]
	v_mfma_f32_16x16x32_bf16 v[50:53], v[142:145], v[186:189], v[50:53]
	v_mfma_f32_16x16x32_bf16 v[42:45], v[150:153], v[186:189], v[42:45]
	v_mfma_f32_16x16x32_bf16 v[34:37], v[142:145], v[202:205], v[34:37]
	v_mfma_f32_16x16x32_bf16 v[26:29], v[150:153], v[202:205], v[26:29]
	v_mfma_f32_16x16x32_bf16 v[18:21], v[142:145], v[210:213], v[18:21]
	v_mfma_f32_16x16x32_bf16 v[10:13], v[150:153], v[210:213], v[10:13]
	s_setprio 0
	s_setprio 1
	v_mfma_f32_16x16x32_bf16 v[54:57], v[158:161], v[174:177], v[54:57]
	v_mfma_f32_16x16x32_bf16 v[46:49], v[166:169], v[174:177], v[46:49]
	v_mfma_f32_16x16x32_bf16 v[38:41], v[158:161], v[182:185], v[38:41]
	v_mfma_f32_16x16x32_bf16 v[30:33], v[166:169], v[182:185], v[30:33]
	v_mfma_f32_16x16x32_bf16 v[22:25], v[158:161], v[190:193], v[22:25]
	v_mfma_f32_16x16x32_bf16 v[14:17], v[166:169], v[190:193], v[14:17]
	v_mfma_f32_16x16x32_bf16 v[6:9], v[158:161], v[206:209], v[6:9]
	v_mfma_f32_16x16x32_bf16 v[2:5], v[166:169], v[206:209], v[2:5]
	v_mfma_f32_16x16x32_bf16 v[54:57], v[162:165], v[178:181], v[54:57]
	v_mfma_f32_16x16x32_bf16 v[46:49], v[170:173], v[178:181], v[46:49]
	v_mfma_f32_16x16x32_bf16 v[38:41], v[162:165], v[186:189], v[38:41]
	v_mfma_f32_16x16x32_bf16 v[30:33], v[170:173], v[186:189], v[30:33]
	v_mfma_f32_16x16x32_bf16 v[22:25], v[162:165], v[202:205], v[22:25]
	v_mfma_f32_16x16x32_bf16 v[14:17], v[170:173], v[202:205], v[14:17]
	v_mfma_f32_16x16x32_bf16 v[6:9], v[162:165], v[210:213], v[6:9]
	v_mfma_f32_16x16x32_bf16 v[2:5], v[170:173], v[210:213], v[2:5]
	s_setprio 0
	s_barrier
	s_add_i32 s75, 0, 0x18000
	s_add_i32 s76, 0, 0x1c000
	v_add_u32_e32 v150, s75, v156
	v_add_u32_e32 v170, s76, v156
	ds_read_b128 v[138:141], v150
	ds_read_b128 v[142:145], v150 offset:1024
	ds_read_b128 v[146:149], v150 offset:2048
	ds_read_b128 v[150:153], v150 offset:3072
	ds_read_b128 v[158:161], v170
	ds_read_b128 v[162:165], v170 offset:1024
	ds_read_b128 v[166:169], v170 offset:2048
	ds_read_b128 v[170:173], v170 offset:3072
	s_add_u32 s44, s44, 0x40000
	s_addc_u32 s45, s45, 0
	s_mov_b32 m0, s69
	v_lshl_add_u64 v[214:215], s[44:45], 0, v[130:131]
	ds_read_b128 v[174:177], v157 offset:32768
	ds_read_b128 v[178:181], v157 offset:33792
	ds_read_b128 v[182:185], v157 offset:34816
	ds_read_b128 v[186:189], v157 offset:35840
	ds_read_b128 v[190:193], v157 offset:36864
	ds_read_b128 v[202:205], v157 offset:37888
	ds_read_b128 v[206:209], v157 offset:38912
	ds_read_b128 v[210:213], v157 offset:39936
	global_load_lds_dwordx4 v[214:215], off
	v_lshl_add_u64 v[214:215], s[44:45], 0, v[132:133]
	s_mov_b32 m0, s70
	s_nop 0
	global_load_lds_dwordx4 v[214:215], off
	s_waitcnt vmcnt(8)
	s_waitcnt lgkmcnt(0)
	s_barrier
	s_setprio 1
	s_waitcnt lgkmcnt(0)
	v_mfma_f32_16x16x32_bf16 v[126:129], v[138:141], v[174:177], v[126:129]
	v_mfma_f32_16x16x32_bf16 v[122:125], v[146:149], v[174:177], v[122:125]
	v_mfma_f32_16x16x32_bf16 v[114:117], v[138:141], v[182:185], v[114:117]
	v_mfma_f32_16x16x32_bf16 v[106:109], v[146:149], v[182:185], v[106:109]
	v_mfma_f32_16x16x32_bf16 v[98:101], v[138:141], v[190:193], v[98:101]
	v_mfma_f32_16x16x32_bf16 v[90:93], v[146:149], v[190:193], v[90:93]
	v_mfma_f32_16x16x32_bf16 v[82:85], v[138:141], v[206:209], v[82:85]
	v_mfma_f32_16x16x32_bf16 v[74:77], v[146:149], v[206:209], v[74:77]
	v_mfma_f32_16x16x32_bf16 v[126:129], v[142:145], v[178:181], v[126:129]
	v_mfma_f32_16x16x32_bf16 v[122:125], v[150:153], v[178:181], v[122:125]
	v_mfma_f32_16x16x32_bf16 v[114:117], v[142:145], v[186:189], v[114:117]
	v_mfma_f32_16x16x32_bf16 v[106:109], v[150:153], v[186:189], v[106:109]
	v_mfma_f32_16x16x32_bf16 v[98:101], v[142:145], v[202:205], v[98:101]
	v_mfma_f32_16x16x32_bf16 v[90:93], v[150:153], v[202:205], v[90:93]
	v_mfma_f32_16x16x32_bf16 v[82:85], v[142:145], v[210:213], v[82:85]
	v_mfma_f32_16x16x32_bf16 v[74:77], v[150:153], v[210:213], v[74:77]
	s_setprio 0
	s_setprio 1
	v_mfma_f32_16x16x32_bf16 v[118:121], v[158:161], v[174:177], v[118:121]
	v_mfma_f32_16x16x32_bf16 v[110:113], v[166:169], v[174:177], v[110:113]
	v_mfma_f32_16x16x32_bf16 v[102:105], v[158:161], v[182:185], v[102:105]
	v_mfma_f32_16x16x32_bf16 v[94:97], v[166:169], v[182:185], v[94:97]
	v_mfma_f32_16x16x32_bf16 v[86:89], v[158:161], v[190:193], v[86:89]
	v_mfma_f32_16x16x32_bf16 v[78:81], v[166:169], v[190:193], v[78:81]
	v_mfma_f32_16x16x32_bf16 v[70:73], v[158:161], v[206:209], v[70:73]
	v_mfma_f32_16x16x32_bf16 v[66:69], v[166:169], v[206:209], v[66:69]
	v_mfma_f32_16x16x32_bf16 v[118:121], v[162:165], v[178:181], v[118:121]
	v_mfma_f32_16x16x32_bf16 v[110:113], v[170:173], v[178:181], v[110:113]
	v_mfma_f32_16x16x32_bf16 v[102:105], v[162:165], v[186:189], v[102:105]
	v_mfma_f32_16x16x32_bf16 v[94:97], v[170:173], v[186:189], v[94:97]
	v_mfma_f32_16x16x32_bf16 v[86:89], v[162:165], v[202:205], v[86:89]
	v_mfma_f32_16x16x32_bf16 v[78:81], v[170:173], v[202:205], v[78:81]
	v_mfma_f32_16x16x32_bf16 v[70:73], v[162:165], v[210:213], v[70:73]
	v_mfma_f32_16x16x32_bf16 v[66:69], v[170:173], v[210:213], v[66:69]
	s_setprio 0
	s_barrier
	s_add_i32 s44, s75, s15
	v_lshl_add_u64 v[154:155], v[154:155], 0, s[48:49]
	s_mov_b32 m0, s44
	ds_read_b128 v[174:177], v157 offset:49152
	ds_read_b128 v[178:181], v157 offset:50176
	ds_read_b128 v[182:185], v157 offset:51200
	ds_read_b128 v[186:189], v157 offset:52224
	ds_read_b128 v[190:193], v157 offset:53248
	ds_read_b128 v[202:205], v157 offset:54272
	ds_read_b128 v[206:209], v157 offset:55296
	ds_read_b128 v[210:213], v157 offset:56320
	global_load_lds_dwordx4 v[154:155], off
	s_add_i32 m0, s44, 0x2000
	s_add_u32 s42, s42, 0x40080
	v_lshl_add_u64 v[154:155], v[194:195], 0, s[48:49]
	s_addc_u32 s43, s43, 0
	s_add_i32 s44, s76, s15
	global_load_lds_dwordx4 v[154:155], off
	v_lshl_add_u64 v[154:155], s[42:43], 0, v[130:131]
	s_mov_b32 m0, s44
	s_nop 0
	global_load_lds_dwordx4 v[154:155], off
	v_lshl_add_u64 v[154:155], s[42:43], 0, v[132:133]
	s_add_i32 m0, s44, 0x2000
	s_nop 0
	global_load_lds_dwordx4 v[154:155], off
	v_lshl_add_u64 v[154:155], v[198:199], 0, s[48:49]
	s_mov_b32 m0, s71
	s_nop 0
	global_load_lds_dwordx4 v[154:155], off
	v_lshl_add_u64 v[154:155], v[200:201], 0, s[48:49]
	s_mov_b32 m0, s79
	s_nop 0
	global_load_lds_dwordx4 v[154:155], off
	s_waitcnt vmcnt(8)
	s_waitcnt lgkmcnt(0)
	s_barrier
	s_setprio 1
	s_waitcnt lgkmcnt(0)
	v_mfma_f32_16x16x32_bf16 v[62:65], v[138:141], v[174:177], v[62:65]
	v_mfma_f32_16x16x32_bf16 v[58:61], v[146:149], v[174:177], v[58:61]
	v_mfma_f32_16x16x32_bf16 v[50:53], v[138:141], v[182:185], v[50:53]
	v_mfma_f32_16x16x32_bf16 v[42:45], v[146:149], v[182:185], v[42:45]
	v_mfma_f32_16x16x32_bf16 v[34:37], v[138:141], v[190:193], v[34:37]
	v_mfma_f32_16x16x32_bf16 v[26:29], v[146:149], v[190:193], v[26:29]
	v_mfma_f32_16x16x32_bf16 v[18:21], v[138:141], v[206:209], v[18:21]
	v_mfma_f32_16x16x32_bf16 v[10:13], v[146:149], v[206:209], v[10:13]
	v_mfma_f32_16x16x32_bf16 v[62:65], v[142:145], v[178:181], v[62:65]
	v_mfma_f32_16x16x32_bf16 v[58:61], v[150:153], v[178:181], v[58:61]
	v_mfma_f32_16x16x32_bf16 v[50:53], v[142:145], v[186:189], v[50:53]
	v_mfma_f32_16x16x32_bf16 v[42:45], v[150:153], v[186:189], v[42:45]
	v_mfma_f32_16x16x32_bf16 v[34:37], v[142:145], v[202:205], v[34:37]
	v_mfma_f32_16x16x32_bf16 v[26:29], v[150:153], v[202:205], v[26:29]
	v_mfma_f32_16x16x32_bf16 v[18:21], v[142:145], v[210:213], v[18:21]
	v_mfma_f32_16x16x32_bf16 v[10:13], v[150:153], v[210:213], v[10:13]
	s_setprio 0
	s_setprio 1
	v_mfma_f32_16x16x32_bf16 v[54:57], v[158:161], v[174:177], v[54:57]
	v_mfma_f32_16x16x32_bf16 v[46:49], v[166:169], v[174:177], v[46:49]
	v_mfma_f32_16x16x32_bf16 v[38:41], v[158:161], v[182:185], v[38:41]
	v_mfma_f32_16x16x32_bf16 v[30:33], v[166:169], v[182:185], v[30:33]
	v_mfma_f32_16x16x32_bf16 v[22:25], v[158:161], v[190:193], v[22:25]
	v_mfma_f32_16x16x32_bf16 v[14:17], v[166:169], v[190:193], v[14:17]
	v_mfma_f32_16x16x32_bf16 v[6:9], v[158:161], v[206:209], v[6:9]
	v_mfma_f32_16x16x32_bf16 v[2:5], v[166:169], v[206:209], v[2:5]
	v_mfma_f32_16x16x32_bf16 v[54:57], v[162:165], v[178:181], v[54:57]
	v_mfma_f32_16x16x32_bf16 v[46:49], v[170:173], v[178:181], v[46:49]
	v_mfma_f32_16x16x32_bf16 v[38:41], v[162:165], v[186:189], v[38:41]
	v_mfma_f32_16x16x32_bf16 v[30:33], v[170:173], v[186:189], v[30:33]
	v_mfma_f32_16x16x32_bf16 v[22:25], v[162:165], v[202:205], v[22:25]
	v_mfma_f32_16x16x32_bf16 v[14:17], v[170:173], v[202:205], v[14:17]
	v_mfma_f32_16x16x32_bf16 v[6:9], v[162:165], v[210:213], v[6:9]
	v_mfma_f32_16x16x32_bf16 v[2:5], v[170:173], v[210:213], v[2:5]
	s_setprio 0
	s_barrier
	s_add_i32 vcc_hi, vcc_hi, 2
	s_add_u32 s16, s16, 0x100
	s_addc_u32 s17, s17, 0
	s_add_u32 s74, s74, 0x100
	s_addc_u32 vcc_lo, vcc_lo, 0
	s_cmp_gt_u32 vcc_hi, 13
	s_cbranch_scc0 .LBB0_374
	s_ashr_i32 s16, s78, 31
	s_lshr_b32 s16, s16, 26
	s_add_i32 s16, s78, s16
	s_ashr_i32 s42, s16, 6
	s_andn2_b32 s16, s16, 63
	s_sub_i32 s43, s78, s16
	v_mov_b32 v164, v0
	s_cmpk_gt_i32 s78, 0x17f
	v_ashrrev_i32_e32 v161, 8, v164
	v_bfe_u32 v160, v164, 6, 2
	v_and_b32_e32 v162, 15, v164
	v_lshrrev_b32_e32 v158, 4, v164
	v_bfe_u32 v159, v164, 4, 2
	s_mov_b64 s[16:17], -1
	s_mov_b32 s81, 0x8000
	s_mov_b32 s77, 0x7f807f81
	s_movk_i32 s75, 0x410
	s_movk_i32 s76, 0xfbfc
	s_cbranch_scc0 .LBB0_381
	s_lshl_b32 s16, s43, 8
	s_and_b32 s44, s16, 0x700
	s_cmp_gt_u32 s42, 7
	s_mov_b64 s[16:17], -1
	v_lshl_add_u32 v163, v161, 6, s44
	s_cbranch_scc0 .LBB0_378
	v_bfe_u32 v138, v162, 2, 1
	v_lshrrev_b32_e32 v139, 3, v162
	v_and_b32_e32 v140, 3, v162
	v_lshl_add_u32 v139, v139, 2, v140
	v_lshlrev_b32_e32 v138, 5, v138
	v_lshl_add_u32 v138, v159, 2, v138
	v_lshlrev_b32_e32 v138, 4, v138
	v_lshl_add_u32 v138, v139, 1, v138
	v_lshrrev_b32_e32 v140, 6, v164
	v_lshlrev_b32_e32 v140, 11, v140
	v_add_u32_e32 v140, 0x21010, v140
	v_add_u32_e32 v138, v138, v140
	v_and_b32_e32 v141, 63, v164
	v_lshl_add_u32 v139, v141, 4, v140
	v_lshlrev_b32_e32 v141, 4, v141
	v_readfirstlane_b32 s16, v164
	s_nop 0
	s_lshr_b32 s16, s16, 6
	s_lshr_b32 s17, s16, 2
	s_and_b32 s16, s16, 3
	s_lshr_b32 s44, s43, 3
	s_lshl_b32 s44, s44, 3
	s_add_i32 s45, s42, -8
	s_lshl_b32 s45, s45, 2
	s_add_i32 s44, s44, s45
	s_lshr_b32 s45, s16, 1
	s_add_i32 s44, s44, s45
	s_lshl_b32 s44, s44, 7
	s_and_b32 s45, s43, 7
	s_lshl_b32 s45, s45, 4
	s_add_i32 s44, s44, s45
	s_lshl_b32 s45, s17, 2
	s_add_i32 s44, s44, s45
	s_lshl_b32 s44, s44, 1
	s_and_b32 s45, s16, 1
	s_add_i32 s44, s44, s45
	s_lshl_b32 s44, s44, 10
	v_readlane_b32 s82, v255, 39
	v_readlane_b32 s83, v255, 40
	s_add_u32 s82, s82, s44
	s_addc_u32 s83, s83, 0
	v_cvt_pk_bf16_f32 v150, v126, v127
	v_cvt_pk_bf16_f32 v151, v128, v129
	v_cvt_pk_bf16_f32 v152, v122, v123
	v_cvt_pk_bf16_f32 v153, v124, v125
	ds_write_b16 v138, v150
	ds_write_b16_d16_hi v138, v150 offset:16
	ds_write_b16 v138, v151 offset:32
	ds_write_b16_d16_hi v138, v151 offset:48
	ds_write_b16 v138, v152 offset:256
	ds_write_b16_d16_hi v138, v152 offset:272
	ds_write_b16 v138, v153 offset:288
	ds_write_b16_d16_hi v138, v153 offset:304
	ds_read_b128 v[142:145], v139
	v_cvt_pk_bf16_f32 v166, v114, v115
	v_cvt_pk_bf16_f32 v167, v116, v117
	v_cvt_pk_bf16_f32 v168, v106, v107
	v_cvt_pk_bf16_f32 v169, v108, v109
	ds_write_b16 v138, v166
	ds_write_b16_d16_hi v138, v166 offset:16
	ds_write_b16 v138, v167 offset:32
	ds_write_b16_d16_hi v138, v167 offset:48
	ds_write_b16 v138, v168 offset:256
	ds_write_b16_d16_hi v138, v168 offset:272
	ds_write_b16 v138, v169 offset:288
	ds_write_b16_d16_hi v138, v169 offset:304
	ds_read_b128 v[146:149], v139
	s_waitcnt lgkmcnt(9)
	s_add_u32 s20, s82, 0x0
	s_addc_u32 s21, s83, 0
	global_store_dwordx4 v141, v[142:145], s[20:21]
	v_cvt_pk_bf16_f32 v150, v98, v99
	v_cvt_pk_bf16_f32 v151, v100, v101
	v_cvt_pk_bf16_f32 v152, v90, v91
	v_cvt_pk_bf16_f32 v153, v92, v93
	ds_write_b16 v138, v150
	ds_write_b16_d16_hi v138, v150 offset:16
	ds_write_b16 v138, v151 offset:32
	ds_write_b16_d16_hi v138, v151 offset:48
	ds_write_b16 v138, v152 offset:256
	ds_write_b16_d16_hi v138, v152 offset:272
	ds_write_b16 v138, v153 offset:288
	ds_write_b16_d16_hi v138, v153 offset:304
	ds_read_b128 v[142:145], v139
	s_waitcnt lgkmcnt(9)
	s_add_u32 s20, s82, 0x0
	s_addc_u32 s21, s83, 0
	global_store_dwordx4 v141, v[146:149], s[20:21] offset:2048
	v_cvt_pk_bf16_f32 v166, v82, v83
	v_cvt_pk_bf16_f32 v167, v84, v85
	v_cvt_pk_bf16_f32 v168, v74, v75
	v_cvt_pk_bf16_f32 v169, v76, v77
	ds_write_b16 v138, v166
	ds_write_b16_d16_hi v138, v166 offset:16
	ds_write_b16 v138, v167 offset:32
	ds_write_b16_d16_hi v138, v167 offset:48
	ds_write_b16 v138, v168 offset:256
	ds_write_b16_d16_hi v138, v168 offset:272
	ds_write_b16 v138, v169 offset:288
	ds_write_b16_d16_hi v138, v169 offset:304
	ds_read_b128 v[146:149], v139
	s_waitcnt lgkmcnt(9)
	s_add_u32 s20, s82, 0x1000
	s_addc_u32 s21, s83, 0
	global_store_dwordx4 v141, v[142:145], s[20:21]
	v_cvt_pk_bf16_f32 v150, v62, v63
	v_cvt_pk_bf16_f32 v151, v64, v65
	v_cvt_pk_bf16_f32 v152, v58, v59
	v_cvt_pk_bf16_f32 v153, v60, v61
	ds_write_b16 v138, v150
	ds_write_b16_d16_hi v138, v150 offset:16
	ds_write_b16 v138, v151 offset:32
	ds_write_b16_d16_hi v138, v151 offset:48
	ds_write_b16 v138, v152 offset:256
	ds_write_b16_d16_hi v138, v152 offset:272
	ds_write_b16 v138, v153 offset:288
	ds_write_b16_d16_hi v138, v153 offset:304
	ds_read_b128 v[142:145], v139
	s_waitcnt lgkmcnt(9)
	s_add_u32 s20, s82, 0x1000
	s_addc_u32 s21, s83, 0
	global_store_dwordx4 v141, v[146:149], s[20:21] offset:2048
	v_cvt_pk_bf16_f32 v166, v50, v51
	v_cvt_pk_bf16_f32 v167, v52, v53
	v_cvt_pk_bf16_f32 v168, v42, v43
	v_cvt_pk_bf16_f32 v169, v44, v45
	ds_write_b16 v138, v166
	ds_write_b16_d16_hi v138, v166 offset:16
	ds_write_b16 v138, v167 offset:32
	ds_write_b16_d16_hi v138, v167 offset:48
	ds_write_b16 v138, v168 offset:256
	ds_write_b16_d16_hi v138, v168 offset:272
	ds_write_b16 v138, v169 offset:288
	ds_write_b16_d16_hi v138, v169 offset:304
	ds_read_b128 v[146:149], v139
	s_waitcnt lgkmcnt(9)
	s_add_u32 s20, s82, 0x4000
	s_addc_u32 s21, s83, 0
	global_store_dwordx4 v141, v[142:145], s[20:21]
	v_cvt_pk_bf16_f32 v150, v34, v35
	v_cvt_pk_bf16_f32 v151, v36, v37
	v_cvt_pk_bf16_f32 v152, v26, v27
	v_cvt_pk_bf16_f32 v153, v28, v29
	ds_write_b16 v138, v150
	ds_write_b16_d16_hi v138, v150 offset:16
	ds_write_b16 v138, v151 offset:32
	ds_write_b16_d16_hi v138, v151 offset:48
	ds_write_b16 v138, v152 offset:256
	ds_write_b16_d16_hi v138, v152 offset:272
	ds_write_b16 v138, v153 offset:288
	ds_write_b16_d16_hi v138, v153 offset:304
	ds_read_b128 v[142:145], v139
	s_waitcnt lgkmcnt(9)
	s_add_u32 s20, s82, 0x4000
	s_addc_u32 s21, s83, 0
	global_store_dwordx4 v141, v[146:149], s[20:21] offset:2048
	v_cvt_pk_bf16_f32 v166, v18, v19
	v_cvt_pk_bf16_f32 v167, v20, v21
	v_cvt_pk_bf16_f32 v168, v10, v11
	v_cvt_pk_bf16_f32 v169, v12, v13
	ds_write_b16 v138, v166
	ds_write_b16_d16_hi v138, v166 offset:16
	ds_write_b16 v138, v167 offset:32
	ds_write_b16_d16_hi v138, v167 offset:48
	ds_write_b16 v138, v168 offset:256
	ds_write_b16_d16_hi v138, v168 offset:272
	ds_write_b16 v138, v169 offset:288
	ds_write_b16_d16_hi v138, v169 offset:304
	ds_read_b128 v[146:149], v139
	s_waitcnt lgkmcnt(9)
	s_add_u32 s20, s82, 0x5000
	s_addc_u32 s21, s83, 0
	global_store_dwordx4 v141, v[142:145], s[20:21]
	v_cvt_pk_bf16_f32 v150, v118, v119
	v_cvt_pk_bf16_f32 v151, v120, v121
	v_cvt_pk_bf16_f32 v152, v110, v111
	v_cvt_pk_bf16_f32 v153, v112, v113
	ds_write_b16 v138, v150
	ds_write_b16_d16_hi v138, v150 offset:16
	ds_write_b16 v138, v151 offset:32
	ds_write_b16_d16_hi v138, v151 offset:48
	ds_write_b16 v138, v152 offset:256
	ds_write_b16_d16_hi v138, v152 offset:272
	ds_write_b16 v138, v153 offset:288
	ds_write_b16_d16_hi v138, v153 offset:304
	ds_read_b128 v[142:145], v139
	s_waitcnt lgkmcnt(9)
	s_add_u32 s20, s82, 0x5000
	s_addc_u32 s21, s83, 0
	global_store_dwordx4 v141, v[146:149], s[20:21] offset:2048
	v_cvt_pk_bf16_f32 v166, v102, v103
	v_cvt_pk_bf16_f32 v167, v104, v105
	v_cvt_pk_bf16_f32 v168, v94, v95
	v_cvt_pk_bf16_f32 v169, v96, v97
	ds_write_b16 v138, v166
	ds_write_b16_d16_hi v138, v166 offset:16
	ds_write_b16 v138, v167 offset:32
	ds_write_b16_d16_hi v138, v167 offset:48
	ds_write_b16 v138, v168 offset:256
	ds_write_b16_d16_hi v138, v168 offset:272
	ds_write_b16 v138, v169 offset:288
	ds_write_b16_d16_hi v138, v169 offset:304
	ds_read_b128 v[146:149], v139
	s_waitcnt lgkmcnt(9)
	s_add_u32 s20, s82, 0x80000
	s_addc_u32 s21, s83, 0
	global_store_dwordx4 v141, v[142:145], s[20:21]
	v_cvt_pk_bf16_f32 v150, v86, v87
	v_cvt_pk_bf16_f32 v151, v88, v89
	v_cvt_pk_bf16_f32 v152, v78, v79
	v_cvt_pk_bf16_f32 v153, v80, v81
	ds_write_b16 v138, v150
	ds_write_b16_d16_hi v138, v150 offset:16
	ds_write_b16 v138, v151 offset:32
	ds_write_b16_d16_hi v138, v151 offset:48
	ds_write_b16 v138, v152 offset:256
	ds_write_b16_d16_hi v138, v152 offset:272
	ds_write_b16 v138, v153 offset:288
	ds_write_b16_d16_hi v138, v153 offset:304
	ds_read_b128 v[142:145], v139
	s_waitcnt lgkmcnt(9)
	s_add_u32 s20, s82, 0x80000
	s_addc_u32 s21, s83, 0
	global_store_dwordx4 v141, v[146:149], s[20:21] offset:2048
	v_cvt_pk_bf16_f32 v166, v70, v71
	v_cvt_pk_bf16_f32 v167, v72, v73
	v_cvt_pk_bf16_f32 v168, v66, v67
	v_cvt_pk_bf16_f32 v169, v68, v69
	ds_write_b16 v138, v166
	ds_write_b16_d16_hi v138, v166 offset:16
	ds_write_b16 v138, v167 offset:32
	ds_write_b16_d16_hi v138, v167 offset:48
	ds_write_b16 v138, v168 offset:256
	ds_write_b16_d16_hi v138, v168 offset:272
	ds_write_b16 v138, v169 offset:288
	ds_write_b16_d16_hi v138, v169 offset:304
	ds_read_b128 v[146:149], v139
	s_waitcnt lgkmcnt(9)
	s_add_u32 s20, s82, 0x81000
	s_addc_u32 s21, s83, 0
	global_store_dwordx4 v141, v[142:145], s[20:21]
	v_cvt_pk_bf16_f32 v150, v54, v55
	v_cvt_pk_bf16_f32 v151, v56, v57
	v_cvt_pk_bf16_f32 v152, v46, v47
	v_cvt_pk_bf16_f32 v153, v48, v49
	ds_write_b16 v138, v150
	ds_write_b16_d16_hi v138, v150 offset:16
	ds_write_b16 v138, v151 offset:32
	ds_write_b16_d16_hi v138, v151 offset:48
	ds_write_b16 v138, v152 offset:256
	ds_write_b16_d16_hi v138, v152 offset:272
	ds_write_b16 v138, v153 offset:288
	ds_write_b16_d16_hi v138, v153 offset:304
	ds_read_b128 v[142:145], v139
	s_waitcnt lgkmcnt(9)
	s_add_u32 s20, s82, 0x81000
	s_addc_u32 s21, s83, 0
	global_store_dwordx4 v141, v[146:149], s[20:21] offset:2048
	v_cvt_pk_bf16_f32 v166, v38, v39
	v_cvt_pk_bf16_f32 v167, v40, v41
	v_cvt_pk_bf16_f32 v168, v30, v31
	v_cvt_pk_bf16_f32 v169, v32, v33
	ds_write_b16 v138, v166
	ds_write_b16_d16_hi v138, v166 offset:16
	ds_write_b16 v138, v167 offset:32
	ds_write_b16_d16_hi v138, v167 offset:48
	ds_write_b16 v138, v168 offset:256
	ds_write_b16_d16_hi v138, v168 offset:272
	ds_write_b16 v138, v169 offset:288
	ds_write_b16_d16_hi v138, v169 offset:304
	ds_read_b128 v[146:149], v139
	s_waitcnt lgkmcnt(9)
	s_add_u32 s20, s82, 0x84000
	s_addc_u32 s21, s83, 0
	global_store_dwordx4 v141, v[142:145], s[20:21]
	v_cvt_pk_bf16_f32 v150, v22, v23
	v_cvt_pk_bf16_f32 v151, v24, v25
	v_cvt_pk_bf16_f32 v152, v14, v15
	v_cvt_pk_bf16_f32 v153, v16, v17
	ds_write_b16 v138, v150
	ds_write_b16_d16_hi v138, v150 offset:16
	ds_write_b16 v138, v151 offset:32
	ds_write_b16_d16_hi v138, v151 offset:48
	ds_write_b16 v138, v152 offset:256
	ds_write_b16_d16_hi v138, v152 offset:272
	ds_write_b16 v138, v153 offset:288
	ds_write_b16_d16_hi v138, v153 offset:304
	ds_read_b128 v[142:145], v139
	s_waitcnt lgkmcnt(9)
	s_add_u32 s20, s82, 0x84000
	s_addc_u32 s21, s83, 0
	global_store_dwordx4 v141, v[146:149], s[20:21] offset:2048
	v_cvt_pk_bf16_f32 v166, v6, v7
	v_cvt_pk_bf16_f32 v167, v8, v9
	v_cvt_pk_bf16_f32 v168, v2, v3
	v_cvt_pk_bf16_f32 v169, v4, v5
	ds_write_b16 v138, v166
	ds_write_b16_d16_hi v138, v166 offset:16
	ds_write_b16 v138, v167 offset:32
	ds_write_b16_d16_hi v138, v167 offset:48
	ds_write_b16 v138, v168 offset:256
	ds_write_b16_d16_hi v138, v168 offset:272
	ds_write_b16 v138, v169 offset:288
	ds_write_b16_d16_hi v138, v169 offset:304
	ds_read_b128 v[146:149], v139
	s_waitcnt lgkmcnt(9)
	s_add_u32 s20, s82, 0x85000
	s_addc_u32 s21, s83, 0
	global_store_dwordx4 v141, v[142:145], s[20:21]
	s_waitcnt lgkmcnt(0)
	s_add_u32 s20, s82, 0x85000
	s_addc_u32 s21, s83, 0
	global_store_dwordx4 v141, v[146:149], s[20:21] offset:2048
	s_mov_b64 s[20:21], 0x1fc0080
	s_mov_b64 s[16:17], 0
	s_mov_b32 s67, 16
.LBB0_378:
	s_andn2_b64 vcc, exec, s[16:17]
	s_cbranch_vccnz .LBB0_380
	s_lshl_b32 s17, s42, 8
	s_addk_i32 s17, 0xfa00
	v_lshl_or_b32 v138, v160, 5, s17
	s_and_b32 s16, s43, 56
	v_lshrrev_b32_e32 v138, 6, v138
	v_add_u32_e32 v140, s16, v138
	v_mov_b32_e32 v141, v196
	v_readlane_b32 s16, v255, 41
	v_lshlrev_b64 v[138:139], 18, v[140:141]
	v_readlane_b32 s17, v255, 42
	v_lshlrev_b32_e32 v141, 11, v160
	v_and_b32_e32 v142, 0x800, v141
	v_lshl_add_u64 v[138:139], s[16:17], 0, v[138:139]
	v_mov_b32_e32 v143, v196
	v_lshlrev_b32_e32 v141, 4, v164
	v_lshl_add_u64 v[138:139], v[138:139], 0, v[142:143]
	v_and_b32_e32 v144, 0x200, v141
	v_mov_b32_e32 v145, v196
	v_lshlrev_b32_e32 v141, 3, v158
	v_ashrrev_i32_e32 v152, 5, v163
	v_lshl_add_u64 v[138:139], v[138:139], 0, v[144:145]
	v_and_b32_e32 v146, 8, v141
	v_mov_b32_e32 v147, v196
	v_ashrrev_i32_e32 v153, 31, v152
	v_lshl_add_u64 v[148:149], v[138:139], 0, v[146:147]
	v_lshlrev_b64 v[154:155], 12, v[152:153]
	v_or_b32_e32 v152, 1, v152
	v_lshl_add_u64 v[164:165], v[148:149], 0, v[154:155]
	v_lshlrev_b32_e32 v138, 4, v162
	v_mov_b32_e32 v139, v196
	v_ashrrev_i32_e32 v153, 31, v152
	v_cvt_pk_bf16_f32 v150, v126, v127
	v_cvt_pk_bf16_f32 v151, v128, v129
	v_lshl_add_u64 v[164:165], v[164:165], 0, v[138:139]
	v_lshlrev_b64 v[152:153], 12, v[152:153]
	global_store_dwordx2 v[164:165], v[150:151], off
	v_cvt_pk_bf16_f32 v150, v114, v115
	v_cvt_pk_bf16_f32 v151, v116, v117
	v_lshl_add_u64 v[166:167], v[148:149], 0, v[152:153]
	global_store_dwordx2 v[164:165], v[150:151], off offset:256
	v_cvt_pk_bf16_f32 v150, v98, v99
	v_cvt_pk_bf16_f32 v151, v100, v101
	v_lshl_add_u64 v[166:167], v[166:167], 0, v[138:139]
	global_store_dwordx2 v[166:167], v[150:151], off
	v_cvt_pk_bf16_f32 v150, v82, v83
	v_cvt_pk_bf16_f32 v151, v84, v85
	global_store_dwordx2 v[166:167], v[150:151], off offset:256
	v_cvt_pk_bf16_f32 v150, v122, v123
	v_cvt_pk_bf16_f32 v151, v124, v125
	global_store_dwordx2 v[164:165], v[150:151], off offset:1024
	v_cvt_pk_bf16_f32 v150, v106, v107
	v_cvt_pk_bf16_f32 v151, v108, v109
	global_store_dwordx2 v[164:165], v[150:151], off offset:1280
	v_cvt_pk_bf16_f32 v164, v90, v91
	v_add_u32_e32 v141, 0x80, v163
	v_cvt_pk_bf16_f32 v165, v92, v93
	global_store_dwordx2 v[166:167], v[164:165], off offset:1024
	v_cvt_pk_bf16_f32 v164, v74, v75
	v_cvt_pk_bf16_f32 v165, v76, v77
	global_store_dwordx2 v[166:167], v[164:165], off offset:1280
	v_ashrrev_i32_e32 v164, 5, v141
	v_ashrrev_i32_e32 v165, 31, v164
	v_lshlrev_b64 v[164:165], 12, v[164:165]
	v_lshl_add_u64 v[166:167], v[148:149], 0, v[164:165]
	v_cvt_pk_bf16_f32 v150, v62, v63
	v_cvt_pk_bf16_f32 v151, v64, v65
	v_lshl_add_u64 v[166:167], v[166:167], 0, v[138:139]
	v_add_u32_e32 v141, 0x90, v163
	global_store_dwordx2 v[166:167], v[150:151], off
	v_cvt_pk_bf16_f32 v150, v58, v59
	v_cvt_pk_bf16_f32 v151, v60, v61
	global_store_dwordx2 v[166:167], v[150:151], off offset:1024
	v_ashrrev_i32_e32 v166, 5, v141
	v_ashrrev_i32_e32 v167, 31, v166
	v_lshlrev_b64 v[166:167], 12, v[166:167]
	v_lshl_add_u64 v[168:169], v[148:149], 0, v[166:167]
	v_cvt_pk_bf16_f32 v150, v50, v51
	v_cvt_pk_bf16_f32 v151, v52, v53
	v_lshl_add_u64 v[168:169], v[168:169], 0, v[138:139]
	v_add_u32_e32 v141, 0xa0, v163
	global_store_dwordx2 v[168:169], v[150:151], off offset:256
	v_cvt_pk_bf16_f32 v150, v42, v43
	v_cvt_pk_bf16_f32 v151, v44, v45
	global_store_dwordx2 v[168:169], v[150:151], off offset:1280
	v_ashrrev_i32_e32 v168, 5, v141
	v_ashrrev_i32_e32 v169, 31, v168
	v_lshlrev_b64 v[168:169], 12, v[168:169]
	v_lshl_add_u64 v[170:171], v[148:149], 0, v[168:169]
	v_cvt_pk_bf16_f32 v150, v34, v35
	v_cvt_pk_bf16_f32 v151, v36, v37
	v_lshl_add_u64 v[170:171], v[170:171], 0, v[138:139]
	v_add_u32_e32 v141, 0xb0, v163
	global_store_dwordx2 v[170:171], v[150:151], off
	v_cvt_pk_bf16_f32 v150, v26, v27
	v_cvt_pk_bf16_f32 v151, v28, v29
	global_store_dwordx2 v[170:171], v[150:151], off offset:1024
	v_ashrrev_i32_e32 v170, 5, v141
	v_or_b32_e32 v140, 2, v140
	v_mov_b32_e32 v141, v196
	v_ashrrev_i32_e32 v171, 31, v170
	v_lshlrev_b64 v[140:141], 18, v[140:141]
	v_lshlrev_b64 v[170:171], 12, v[170:171]
	v_lshl_add_u64 v[140:141], s[16:17], 0, v[140:141]
	v_lshl_add_u64 v[148:149], v[148:149], 0, v[170:171]
	v_lshl_add_u64 v[140:141], v[140:141], 0, v[142:143]
	v_cvt_pk_bf16_f32 v150, v18, v19
	v_cvt_pk_bf16_f32 v151, v20, v21
	v_lshl_add_u64 v[148:149], v[148:149], 0, v[138:139]
	v_lshl_add_u64 v[140:141], v[140:141], 0, v[144:145]
	global_store_dwordx2 v[148:149], v[150:151], off offset:256
	v_cvt_pk_bf16_f32 v150, v10, v11
	v_cvt_pk_bf16_f32 v151, v12, v13
	v_lshl_add_u64 v[140:141], v[140:141], 0, v[146:147]
	global_store_dwordx2 v[148:149], v[150:151], off offset:1280
	v_lshl_add_u64 v[144:145], v[140:141], 0, v[154:155]
	v_lshl_add_u64 v[146:147], v[140:141], 0, v[152:153]
	v_lshl_add_u64 v[148:149], v[140:141], 0, v[164:165]
	v_lshl_add_u64 v[150:151], v[140:141], 0, v[166:167]
	v_lshl_add_u64 v[152:153], v[140:141], 0, v[168:169]
	v_lshl_add_u64 v[140:141], v[140:141], 0, v[170:171]
	v_cvt_pk_bf16_f32 v142, v118, v119
	v_cvt_pk_bf16_f32 v143, v120, v121
	v_lshl_add_u64 v[144:145], v[144:145], 0, v[138:139]
	v_lshl_add_u64 v[146:147], v[146:147], 0, v[138:139]
	v_lshl_add_u64 v[148:149], v[148:149], 0, v[138:139]
	v_lshl_add_u64 v[150:151], v[150:151], 0, v[138:139]
	v_lshl_add_u64 v[152:153], v[152:153], 0, v[138:139]
	v_lshl_add_u64 v[138:139], v[140:141], 0, v[138:139]
	v_cvt_pk_bf16_f32 v140, v110, v111
	v_cvt_pk_bf16_f32 v141, v112, v113
	global_store_dwordx2 v[144:145], v[142:143], off
	v_cvt_pk_bf16_f32 v142, v102, v103
	v_cvt_pk_bf16_f32 v143, v104, v105
	global_store_dwordx2 v[144:145], v[140:141], off offset:1024
	v_cvt_pk_bf16_f32 v140, v94, v95
	v_cvt_pk_bf16_f32 v141, v96, v97
	global_store_dwordx2 v[144:145], v[142:143], off offset:256
	v_cvt_pk_bf16_f32 v142, v86, v87
	v_cvt_pk_bf16_f32 v143, v88, v89
	global_store_dwordx2 v[144:145], v[140:141], off offset:1280
	v_cvt_pk_bf16_f32 v140, v78, v79
	v_cvt_pk_bf16_f32 v141, v80, v81
	global_store_dwordx2 v[146:147], v[142:143], off
	v_cvt_pk_bf16_f32 v142, v70, v71
	v_cvt_pk_bf16_f32 v143, v72, v73
	global_store_dwordx2 v[146:147], v[140:141], off offset:1024
	v_cvt_pk_bf16_f32 v140, v66, v67
	v_cvt_pk_bf16_f32 v141, v68, v69
	global_store_dwordx2 v[146:147], v[142:143], off offset:256
	v_cvt_pk_bf16_f32 v142, v54, v55
	v_cvt_pk_bf16_f32 v143, v56, v57
	global_store_dwordx2 v[146:147], v[140:141], off offset:1280
	v_cvt_pk_bf16_f32 v140, v46, v47
	v_cvt_pk_bf16_f32 v141, v48, v49
	global_store_dwordx2 v[148:149], v[142:143], off
	v_cvt_pk_bf16_f32 v142, v38, v39
	v_cvt_pk_bf16_f32 v143, v40, v41
	global_store_dwordx2 v[148:149], v[140:141], off offset:1024
	v_cvt_pk_bf16_f32 v140, v30, v31
	v_cvt_pk_bf16_f32 v141, v32, v33
	global_store_dwordx2 v[150:151], v[142:143], off offset:256
	v_cvt_pk_bf16_f32 v142, v22, v23
	v_cvt_pk_bf16_f32 v143, v24, v25
	global_store_dwordx2 v[150:151], v[140:141], off offset:1280
	v_cvt_pk_bf16_f32 v140, v14, v15
	v_cvt_pk_bf16_f32 v141, v16, v17
	global_store_dwordx2 v[152:153], v[142:143], off
	v_cvt_pk_bf16_f32 v142, v6, v7
	v_cvt_pk_bf16_f32 v143, v8, v9
	global_store_dwordx2 v[138:139], v[142:143], off offset:256
	global_store_dwordx2 v[152:153], v[140:141], off offset:1024
	v_cvt_pk_bf16_f32 v140, v2, v3
	v_cvt_pk_bf16_f32 v141, v4, v5
	global_store_dwordx2 v[138:139], v[140:141], off offset:1280
	s_mov_b32 s67, 32

.LBB0_381:
	s_andn2_b64 vcc, exec, s[16:17]
	s_cbranch_vccnz .LBB0_368
	v_lshl_or_b32 v138, s43, 8, v162
	v_lshl_add_u32 v144, v161, 6, v138
	s_lshl_b32 s16, s42, 8
	s_ashr_i32 s17, s16, 31
	v_mov_b64_e32 v[138:139], s[60:61]
	s_movk_i32 s44, 0xc00
	v_cvt_pk_bf16_f32 v70, v70, v71
	v_cvt_pk_bf16_f32 v71, v72, v73
	v_cvt_pk_bf16_f32 v72, v66, v67
	v_add_u32_e32 v66, 0x80, v144
	v_mad_i64_i32 v[140:141], s[42:43], v144, s44, v[138:139]
	s_lshl_b64 s[16:17], s[16:17], 1
	v_mad_i64_i32 v[66:67], s[42:43], v66, s44, v[138:139]
	v_lshl_add_u64 v[142:143], v[140:141], 0, s[16:17]
	v_lshlrev_b32_e32 v140, 6, v160
	v_mov_b32_e32 v141, v196
	v_cvt_pk_bf16_f32 v126, v126, v127
	v_cvt_pk_bf16_f32 v127, v128, v129
	v_cvt_pk_bf16_f32 v128, v122, v123
	v_lshlrev_b32_e32 v122, 5, v159
	v_lshl_add_u64 v[66:67], v[66:67], 0, s[16:17]
	v_lshl_add_u64 v[142:143], v[142:143], 0, v[140:141]
	v_cvt_pk_bf16_f32 v129, v124, v125
	v_and_b32_e32 v122, 32, v122
	v_mov_b32_e32 v123, v196
	v_lshlrev_b32_e32 v124, 3, v158
	v_cvt_pk_bf16_f32 v118, v118, v119
	v_cvt_pk_bf16_f32 v119, v120, v121
	v_cvt_pk_bf16_f32 v120, v110, v111
	v_or_b32_e32 v110, 16, v144
	v_lshl_add_u64 v[66:67], v[66:67], 0, v[140:141]
	v_cvt_pk_bf16_f32 v54, v54, v55
	v_cvt_pk_bf16_f32 v55, v56, v57
	v_cvt_pk_bf16_f32 v56, v46, v47
	v_add_u32_e32 v46, 0x90, v144
	v_lshl_add_u64 v[142:143], v[142:143], 0, v[122:123]
	v_and_b32_e32 v124, 16, v124
	v_mov_b32_e32 v125, v196
	v_cvt_pk_bf16_f32 v121, v112, v113
	v_mad_i64_i32 v[110:111], s[42:43], v110, s44, v[138:139]
	v_cvt_pk_bf16_f32 v62, v62, v63
	v_cvt_pk_bf16_f32 v63, v64, v65
	v_cvt_pk_bf16_f32 v64, v58, v59
	v_lshl_add_u64 v[58:59], v[66:67], 0, v[122:123]
	v_cvt_pk_bf16_f32 v57, v48, v49
	v_mad_i64_i32 v[46:47], s[42:43], v46, s44, v[138:139]
	v_lshl_add_u64 v[142:143], v[142:143], 0, v[124:125]
	v_permlane16_swap_b32_e32 v118, v120
	v_permlane16_swap_b32_e32 v119, v121
	v_lshl_add_u64 v[110:111], v[110:111], 0, s[16:17]
	v_lshl_add_u64 v[58:59], v[58:59], 0, v[124:125]
	v_permlane16_swap_b32_e32 v54, v56
	v_permlane16_swap_b32_e32 v55, v57
	v_lshl_add_u64 v[46:47], v[46:47], 0, s[16:17]
	global_store_dwordx4 v[142:143], v[118:121], off offset:256
	v_cvt_pk_bf16_f32 v102, v102, v103
	v_cvt_pk_bf16_f32 v103, v104, v105
	v_cvt_pk_bf16_f32 v104, v94, v95
	v_or_b32_e32 v94, 32, v144
	global_store_dwordx4 v[58:59], v[54:57], off offset:256
	v_lshl_add_u64 v[118:119], v[110:111], 0, v[140:141]
	v_cvt_pk_bf16_f32 v38, v38, v39
	v_cvt_pk_bf16_f32 v39, v40, v41
	v_cvt_pk_bf16_f32 v40, v30, v31
	v_add_u32_e32 v30, 0xa0, v144
	v_lshl_add_u64 v[54:55], v[46:47], 0, v[140:141]
	v_cvt_pk_bf16_f32 v112, v106, v107
	v_lshl_add_u64 v[106:107], v[118:119], 0, v[122:123]
	v_cvt_pk_bf16_f32 v105, v96, v97
	v_mad_i64_i32 v[94:95], s[42:43], v94, s44, v[138:139]
	v_cvt_pk_bf16_f32 v48, v42, v43
	v_lshl_add_u64 v[42:43], v[54:55], 0, v[122:123]
	v_cvt_pk_bf16_f32 v41, v32, v33
	v_mad_i64_i32 v[30:31], s[42:43], v30, s44, v[138:139]
	v_lshl_add_u64 v[106:107], v[106:107], 0, v[124:125]
	v_permlane16_swap_b32_e32 v102, v104
	v_permlane16_swap_b32_e32 v103, v105
	v_lshl_add_u64 v[94:95], v[94:95], 0, s[16:17]
	v_lshl_add_u64 v[42:43], v[42:43], 0, v[124:125]
	v_permlane16_swap_b32_e32 v38, v40
	v_permlane16_swap_b32_e32 v39, v41
	v_lshl_add_u64 v[30:31], v[30:31], 0, s[16:17]
	global_store_dwordx4 v[106:107], v[102:105], off offset:256
	v_cvt_pk_bf16_f32 v86, v86, v87
	v_cvt_pk_bf16_f32 v87, v88, v89
	v_cvt_pk_bf16_f32 v88, v78, v79
	v_or_b32_e32 v78, 48, v144
	global_store_dwordx4 v[42:43], v[38:41], off offset:256
	v_lshl_add_u64 v[102:103], v[94:95], 0, v[140:141]
	v_cvt_pk_bf16_f32 v22, v22, v23
	v_cvt_pk_bf16_f32 v23, v24, v25
	v_cvt_pk_bf16_f32 v24, v14, v15
	v_add_u32_e32 v14, 0xb0, v144
	v_lshl_add_u64 v[38:39], v[30:31], 0, v[140:141]
	v_cvt_pk_bf16_f32 v96, v90, v91
	v_lshl_add_u64 v[90:91], v[102:103], 0, v[122:123]
	v_cvt_pk_bf16_f32 v89, v80, v81
	v_mad_i64_i32 v[78:79], s[42:43], v78, s44, v[138:139]
	v_cvt_pk_bf16_f32 v32, v26, v27
	v_lshl_add_u64 v[26:27], v[38:39], 0, v[122:123]
	v_cvt_pk_bf16_f32 v25, v16, v17
	v_mad_i64_i32 v[14:15], s[42:43], v14, s44, v[138:139]
	v_lshl_add_u64 v[90:91], v[90:91], 0, v[124:125]
	v_permlane16_swap_b32_e32 v86, v88
	v_permlane16_swap_b32_e32 v87, v89
	v_lshl_add_u64 v[78:79], v[78:79], 0, s[16:17]
	v_lshl_add_u64 v[26:27], v[26:27], 0, v[124:125]
	v_permlane16_swap_b32_e32 v22, v24
	v_permlane16_swap_b32_e32 v23, v25
	v_lshl_add_u64 v[14:15], v[14:15], 0, s[16:17]
	global_store_dwordx4 v[90:91], v[86:89], off offset:256
	global_store_dwordx4 v[26:27], v[22:25], off offset:256
	v_cvt_pk_bf16_f32 v110, v114, v115
	v_cvt_pk_bf16_f32 v111, v116, v117
	v_cvt_pk_bf16_f32 v113, v108, v109
	v_cvt_pk_bf16_f32 v94, v98, v99
	s_nop 0
	v_lshl_add_u64 v[86:87], v[78:79], 0, v[140:141]
	v_lshl_add_u64 v[22:23], v[14:15], 0, v[140:141]
	v_cvt_pk_bf16_f32 v95, v100, v101
	v_cvt_pk_bf16_f32 v97, v92, v93
	v_cvt_pk_bf16_f32 v78, v82, v83
	v_cvt_pk_bf16_f32 v79, v84, v85
	v_cvt_pk_bf16_f32 v80, v74, v75
	v_cvt_pk_bf16_f32 v81, v76, v77
	v_lshl_add_u64 v[74:75], v[86:87], 0, v[122:123]
	v_cvt_pk_bf16_f32 v73, v68, v69
	v_cvt_pk_bf16_f32 v65, v60, v61
	v_cvt_pk_bf16_f32 v46, v50, v51
	v_cvt_pk_bf16_f32 v47, v52, v53
	v_cvt_pk_bf16_f32 v49, v44, v45
	v_cvt_pk_bf16_f32 v30, v34, v35
	v_cvt_pk_bf16_f32 v31, v36, v37
	v_cvt_pk_bf16_f32 v33, v28, v29
	v_cvt_pk_bf16_f32 v14, v18, v19
	v_cvt_pk_bf16_f32 v15, v20, v21
	v_cvt_pk_bf16_f32 v16, v10, v11
	v_cvt_pk_bf16_f32 v17, v12, v13
	v_lshl_add_u64 v[10:11], v[22:23], 0, v[122:123]
	v_cvt_pk_bf16_f32 v6, v6, v7
	v_cvt_pk_bf16_f32 v7, v8, v9
	v_cvt_pk_bf16_f32 v8, v2, v3
	v_cvt_pk_bf16_f32 v9, v4, v5
	v_permlane16_swap_b32_e32 v126, v128
	v_permlane16_swap_b32_e32 v127, v129
	v_permlane16_swap_b32_e32 v110, v112
	v_permlane16_swap_b32_e32 v111, v113
	v_permlane16_swap_b32_e32 v94, v96
	v_permlane16_swap_b32_e32 v95, v97
	v_permlane16_swap_b32_e32 v78, v80
	v_permlane16_swap_b32_e32 v79, v81
	v_lshl_add_u64 v[74:75], v[74:75], 0, v[124:125]
	v_permlane16_swap_b32_e32 v70, v72
	v_permlane16_swap_b32_e32 v71, v73
	v_permlane16_swap_b32_e32 v62, v64
	v_permlane16_swap_b32_e32 v63, v65
	v_permlane16_swap_b32_e32 v46, v48
	v_permlane16_swap_b32_e32 v47, v49
	v_permlane16_swap_b32_e32 v30, v32
	v_permlane16_swap_b32_e32 v31, v33
	v_permlane16_swap_b32_e32 v14, v16
	v_permlane16_swap_b32_e32 v15, v17
	v_lshl_add_u64 v[10:11], v[10:11], 0, v[124:125]
	v_permlane16_swap_b32_e32 v6, v8
	v_permlane16_swap_b32_e32 v7, v9
	global_store_dwordx4 v[142:143], v[126:129], off
	global_store_dwordx4 v[106:107], v[110:113], off
	global_store_dwordx4 v[90:91], v[94:97], off
	global_store_dwordx4 v[74:75], v[78:81], off
	global_store_dwordx4 v[74:75], v[70:73], off offset:256
	global_store_dwordx4 v[58:59], v[62:65], off
	global_store_dwordx4 v[42:43], v[46:49], off
	global_store_dwordx4 v[26:27], v[30:33], off
	global_store_dwordx4 v[10:11], v[14:17], off
	global_store_dwordx4 v[10:11], v[6:9], off offset:256
	s_mov_b32 s67, 16
	s_branch .LBB0_368
.Lp2_wa_rel:
	s_cmp_eq_u32 s67, 16
	s_cbranch_scc1 .Lp2_wa_16
	s_waitcnt vmcnt(40)
	s_branch .Lp2_wa_done
.Lp2_wa_16:
	s_waitcnt vmcnt(24)
	s_branch .Lp2_wa_done
